# v66 + helper progress-flag poll interval lengthened (s_sleep 12 -> 24)
# baseline (speedup 1.0000x reference)
.Lhflag_4:
	ds_read_b32 v249, v246
	s_waitcnt lgkmcnt(0)
	v_cmp_gt_u32_e32 vcc, s64, v249
	s_nop 0
	s_cbranch_vccz .Lhflag_go_4
	s_sleep 24
	s_branch .Lhflag_4
